# P4 epilogue (EpiOut) rewritten by hand: rowss/h/pp loads of the 8 row groups run 4 groups ahead in rotating register sets so the exp/rcp work overlaps the loads; global ops with counted vmcnt instead
# speedup vs baseline: 1.0078x; 1.0078x over previous
;     __device__ __forceinline__ void operator()(const Acc& acc, const Unit& u, int wr, int wc, int fr, int fq) const {
;     ...
;         const int colbase = u.pn * 256 + wc * 64 + 8 * fq;
; #pragma unroll
;         for (int ai = 0; ai < 2; ++ai) {
;             f32x4 hv[4][2][2]; u32x4 pw[4][2]; float rsv[4];
; #pragma unroll
;             for (int m = 0; m < 4; ++m) { const int row = u.pm * 256 + ai * 128 + wr * 64 + m * 16 + fr; const size_t off = (size_t)row * DM + colbase;
;                 rsv[m] = rowss[row];
; #pragma unroll
;                 for (int bj = 0; bj < 2; ++bj) { const u32x4 hw = __builtin_nontemporal_load((const u32x4*)(hin + off + 32 * bj));
;                     hv[m][bj][0] = (f32x4){bflo(hw.x), bfhi(hw.x), bflo(hw.y), bfhi(hw.y)}; hv[m][bj][1] = (f32x4){bflo(hw.z), bfhi(hw.z), bflo(hw.w), bfhi(hw.w)};
;                     pw[m][bj] = __builtin_nontemporal_load((const u32x4*)(PP + off + 32 * bj)); } }
; #pragma unroll
;             for (int m = 0; m < 4; ++m) {
;                 const int row = u.pm * 256 + ai * 128 + wr * 64 + m * 16 + fr;
;                 const float rs = rsqrtf(rsv[m] * (1.0f / DM) + EPS) * -1.4426950408889634f;
; #pragma unroll
;                 for (int bj = 0; bj < 2; ++bj) {
;                     const size_t off = (size_t)row * DM + colbase + 32 * bj;
;                     f32x4 h0 = hv[m][bj][0], h1 = hv[m][bj][1];
;                     const u32x4 p4 = pw[m][bj];
;                     const f32x4 a0 = acc[ai][bj][m][0], a1 = acc[ai][bj][m][1];
;                     h0.x += bflo(p4.x) * __builtin_amdgcn_rcpf(1.0f + __builtin_amdgcn_exp2f(a0.x * rs));
;                     h0.y += bfhi(p4.x) * __builtin_amdgcn_rcpf(1.0f + __builtin_amdgcn_exp2f(a0.y * rs));
;                     h0.z += bflo(p4.y) * __builtin_amdgcn_rcpf(1.0f + __builtin_amdgcn_exp2f(a0.z * rs));
;                     h0.w += bfhi(p4.y) * __builtin_amdgcn_rcpf(1.0f + __builtin_amdgcn_exp2f(a0.w * rs));
;                     h1.x += bflo(p4.z) * __builtin_amdgcn_rcpf(1.0f + __builtin_amdgcn_exp2f(a1.x * rs));
;                     h1.y += bfhi(p4.z) * __builtin_amdgcn_rcpf(1.0f + __builtin_amdgcn_exp2f(a1.y * rs));
;                     h1.z += bflo(p4.w) * __builtin_amdgcn_rcpf(1.0f + __builtin_amdgcn_exp2f(a1.z * rs));
;                     h1.w += bfhi(p4.w) * __builtin_amdgcn_rcpf(1.0f + __builtin_amdgcn_exp2f(a1.w * rs));
.LBB0_814:
	v_and_b32_e32 v188, 15, v200
	v_bfe_u32 v225, v200, 4, 2
	s_lshl_b32 s11, s42, 8
	s_or_b32 s11, s11, s86
	v_lshl_add_u32 v225, v225, 3, s11
	s_lshl_b32 s11, s41, 8
	s_add_i32 s11, s11, s79
	v_add_u32_e32 v188, s11, v188
	v_lshlrev_b32_e32 v190, 12, v188
	v_lshl_add_u32 v190, v225, 1, v190
	v_lshlrev_b32_e32 v193, 2, v188
	v_lshlrev_b32_e32 v192, 13, v188
	v_lshl_add_u32 v192, v225, 2, v192
	v_mov_b32_e32 v198, v193
	global_load_dword v226, v198, s[80:81]
	v_mov_b32_e32 v194, v190
	global_load_dwordx4 v[128:131], v194, s[6:7] nt
	global_load_dwordx4 v[132:135], v194, s[8:9] nt
	global_load_dwordx4 v[136:139], v194, s[6:7] offset:64 nt
	global_load_dwordx4 v[140:143], v194, s[8:9] offset:64 nt
	v_add_u32_e32 v199, 0x40, v193
	global_load_dword v234, v199, s[80:81]
	v_add_u32_e32 v195, 0x10000, v190
	global_load_dwordx4 v[144:147], v195, s[6:7] nt
	global_load_dwordx4 v[148:151], v195, s[8:9] nt
	global_load_dwordx4 v[152:155], v195, s[6:7] offset:64 nt
	global_load_dwordx4 v[156:159], v195, s[8:9] offset:64 nt
	v_add_u32_e32 v222, 0x80, v193
	global_load_dword v235, v222, s[80:81]
	v_add_u32_e32 v196, 0x20000, v190
	global_load_dwordx4 v[160:163], v196, s[6:7] nt
	global_load_dwordx4 v[164:167], v196, s[8:9] nt
	global_load_dwordx4 v[168:171], v196, s[6:7] offset:64 nt
	global_load_dwordx4 v[172:175], v196, s[8:9] offset:64 nt
	v_add_u32_e32 v223, 0xc0, v193
	global_load_dword v191, v223, s[80:81]
	v_add_u32_e32 v197, 0x30000, v190
	global_load_dwordx4 v[206:209], v197, s[6:7] nt
	global_load_dwordx4 v[210:213], v197, s[8:9] nt
	global_load_dwordx4 v[214:217], v197, s[6:7] offset:64 nt
	global_load_dwordx4 v[218:221], v197, s[8:9] offset:64 nt
	v_mov_b32_e32 v189, v192
	s_waitcnt vmcnt(15)
	v_fmamk_f32 v236, v226, 0x3a000000, v205
	v_mul_f32_e32 v237, 0x4b800000, v236
	v_cmp_gt_f32_e32 vcc, s40, v236
	s_nop 1
	v_cndmask_b32_e32 v236, v236, v237, vcc
	v_rsq_f32_e32 v237, v236
	s_nop 0
	v_mul_f32_e32 v236, 0x45800000, v237
	v_cndmask_b32_e32 v236, v237, v236, vcc
	v_mul_f32_e32 v236, 0xbfb8aa3b, v236
	v_mul_f32_e32 v124, v124, v236
	v_mul_f32_e32 v125, v125, v236
	v_mul_f32_e32 v126, v126, v236
	v_mul_f32_e32 v127, v127, v236
	v_exp_f32_e32 v124, v124
	v_exp_f32_e32 v125, v125
	v_exp_f32_e32 v126, v126
	v_exp_f32_e32 v127, v127
	s_nop 0
	v_add_f32_e32 v124, 1.0, v124
	v_add_f32_e32 v125, 1.0, v125
	v_add_f32_e32 v126, 1.0, v126
	v_add_f32_e32 v127, 1.0, v127
	v_rcp_f32_e32 v124, v124
	v_rcp_f32_e32 v125, v125
	v_rcp_f32_e32 v126, v126
	v_rcp_f32_e32 v127, v127
	v_lshlrev_b32_e32 v238, 16, v128
	v_and_b32_e32 v239, 0xffff0000, v128
	v_lshlrev_b32_e32 v240, 16, v132
	v_and_b32_e32 v241, 0xffff0000, v132
	v_pk_fma_f32 v[124:125], v[124:125], v[240:241], v[238:239]
	v_lshlrev_b32_e32 v238, 16, v129
	v_and_b32_e32 v239, 0xffff0000, v129
	v_lshlrev_b32_e32 v240, 16, v133
	v_and_b32_e32 v241, 0xffff0000, v133
	v_pk_fma_f32 v[126:127], v[126:127], v[240:241], v[238:239]
	v_mul_f32_e32 v120, v120, v236
	v_mul_f32_e32 v121, v121, v236
	v_mul_f32_e32 v122, v122, v236
	v_mul_f32_e32 v123, v123, v236
	v_exp_f32_e32 v120, v120
	v_exp_f32_e32 v121, v121
	v_exp_f32_e32 v122, v122
	v_exp_f32_e32 v123, v123
	s_nop 0
	v_add_f32_e32 v120, 1.0, v120
	v_add_f32_e32 v121, 1.0, v121
	v_add_f32_e32 v122, 1.0, v122
	v_add_f32_e32 v123, 1.0, v123
	v_rcp_f32_e32 v120, v120
	v_rcp_f32_e32 v121, v121
	v_rcp_f32_e32 v122, v122
	v_rcp_f32_e32 v123, v123
	v_lshlrev_b32_e32 v238, 16, v130
	v_and_b32_e32 v239, 0xffff0000, v130
	v_lshlrev_b32_e32 v240, 16, v134
	v_and_b32_e32 v241, 0xffff0000, v134
	v_pk_fma_f32 v[120:121], v[120:121], v[240:241], v[238:239]
	v_lshlrev_b32_e32 v238, 16, v131
	v_and_b32_e32 v239, 0xffff0000, v131
	v_lshlrev_b32_e32 v240, 16, v135
	v_and_b32_e32 v241, 0xffff0000, v135
	v_pk_fma_f32 v[122:123], v[122:123], v[240:241], v[238:239]
	v_mul_f32_e32 v116, v116, v236
	v_mul_f32_e32 v117, v117, v236
	v_mul_f32_e32 v118, v118, v236
	v_mul_f32_e32 v119, v119, v236
	v_exp_f32_e32 v116, v116
	v_exp_f32_e32 v117, v117
	v_exp_f32_e32 v118, v118
	v_exp_f32_e32 v119, v119
	s_nop 0
	v_add_f32_e32 v116, 1.0, v116
	v_add_f32_e32 v117, 1.0, v117
	v_add_f32_e32 v118, 1.0, v118
	v_add_f32_e32 v119, 1.0, v119
	v_rcp_f32_e32 v116, v116
	v_rcp_f32_e32 v117, v117
	v_rcp_f32_e32 v118, v118
	v_rcp_f32_e32 v119, v119
	v_lshlrev_b32_e32 v238, 16, v136
	v_and_b32_e32 v239, 0xffff0000, v136
	v_lshlrev_b32_e32 v240, 16, v140
	v_and_b32_e32 v241, 0xffff0000, v140
	v_pk_fma_f32 v[116:117], v[116:117], v[240:241], v[238:239]
	v_lshlrev_b32_e32 v238, 16, v137
	v_and_b32_e32 v239, 0xffff0000, v137
	v_lshlrev_b32_e32 v240, 16, v141
	v_and_b32_e32 v241, 0xffff0000, v141
	v_pk_fma_f32 v[118:119], v[118:119], v[240:241], v[238:239]
	v_mul_f32_e32 v112, v112, v236
	v_mul_f32_e32 v113, v113, v236
	v_mul_f32_e32 v114, v114, v236
	v_mul_f32_e32 v115, v115, v236
	v_exp_f32_e32 v112, v112
	v_exp_f32_e32 v113, v113
	v_exp_f32_e32 v114, v114
	v_exp_f32_e32 v115, v115
	s_nop 0
	v_add_f32_e32 v112, 1.0, v112
	v_add_f32_e32 v113, 1.0, v113
	v_add_f32_e32 v114, 1.0, v114
	v_add_f32_e32 v115, 1.0, v115
	v_rcp_f32_e32 v112, v112
	v_rcp_f32_e32 v113, v113
	v_rcp_f32_e32 v114, v114
	v_rcp_f32_e32 v115, v115
	v_lshlrev_b32_e32 v238, 16, v138
	v_and_b32_e32 v239, 0xffff0000, v138
	v_lshlrev_b32_e32 v240, 16, v142
	v_and_b32_e32 v241, 0xffff0000, v142
	v_pk_fma_f32 v[112:113], v[112:113], v[240:241], v[238:239]
	v_lshlrev_b32_e32 v238, 16, v139
	v_and_b32_e32 v239, 0xffff0000, v139
	v_lshlrev_b32_e32 v240, 16, v143
	v_and_b32_e32 v241, 0xffff0000, v143
	v_pk_fma_f32 v[114:115], v[114:115], v[240:241], v[238:239]
	global_store_dwordx4 v189, v[124:127], s[2:3]
	global_store_dwordx4 v189, v[120:123], s[2:3] offset:16
	global_store_dwordx4 v189, v[116:119], s[2:3] offset:128
	global_store_dwordx4 v189, v[112:115], s[2:3] offset:144
	v_add_u32_e32 v198, 0x200, v193
	global_load_dword v226, v198, s[80:81]
	v_add_u32_e32 v194, 0x80000, v190
	global_load_dwordx4 v[128:131], v194, s[6:7] nt
	global_load_dwordx4 v[132:135], v194, s[8:9] nt
	global_load_dwordx4 v[136:139], v194, s[6:7] offset:64 nt
	global_load_dwordx4 v[140:143], v194, s[8:9] offset:64 nt
	v_add_u32_e32 v224, 0x20000, v192
	s_waitcnt vmcnt(19)
; __device__ __forceinline__ float bflo(unsigned u) { return __uint_as_float(u << 16); }
; __device__ __forceinline__ float bfhi(unsigned u) { return __uint_as_float(u & 0xffff0000u); }
;     __device__ __forceinline__ void operator()(const Acc& acc, const Unit& u, int wr, int wc, int fr, int fq) const {
;     ...
;             for (int m = 0; m < 4; ++m) {
;                 const int row = u.pm * 256 + ai * 128 + wr * 64 + m * 16 + fr;
;                 const float rs = rsqrtf(rsv[m] * (1.0f / DM) + EPS) * -1.4426950408889634f;
; #pragma unroll
;                 for (int bj = 0; bj < 2; ++bj) {
;                     const size_t off = (size_t)row * DM + colbase + 32 * bj;
;                     f32x4 h0 = hv[m][bj][0], h1 = hv[m][bj][1];
;                     const u32x4 p4 = pw[m][bj];
;                     const f32x4 a0 = acc[ai][bj][m][0], a1 = acc[ai][bj][m][1];
;                     h0.x += bflo(p4.x) * __builtin_amdgcn_rcpf(1.0f + __builtin_amdgcn_exp2f(a0.x * rs));
;                     h0.y += bfhi(p4.x) * __builtin_amdgcn_rcpf(1.0f + __builtin_amdgcn_exp2f(a0.y * rs));
;                     h0.z += bflo(p4.y) * __builtin_amdgcn_rcpf(1.0f + __builtin_amdgcn_exp2f(a0.z * rs));
;                     h0.w += bfhi(p4.y) * __builtin_amdgcn_rcpf(1.0f + __builtin_amdgcn_exp2f(a0.w * rs));
;                     h1.x += bflo(p4.z) * __builtin_amdgcn_rcpf(1.0f + __builtin_amdgcn_exp2f(a1.x * rs));
;                     h1.y += bfhi(p4.z) * __builtin_amdgcn_rcpf(1.0f + __builtin_amdgcn_exp2f(a1.y * rs));
;                     h1.z += bflo(p4.w) * __builtin_amdgcn_rcpf(1.0f + __builtin_amdgcn_exp2f(a1.z * rs));
;                     h1.w += bfhi(p4.w) * __builtin_amdgcn_rcpf(1.0f + __builtin_amdgcn_exp2f(a1.w * rs));
;                     *(f32x4*)(out + off) = h0; *(f32x4*)(out + off + 4) = h1;
;                 }
	v_fmamk_f32 v236, v234, 0x3a000000, v205
	v_mul_f32_e32 v237, 0x4b800000, v236
	v_cmp_gt_f32_e32 vcc, s40, v236
	s_nop 1
	v_cndmask_b32_e32 v236, v236, v237, vcc
	v_rsq_f32_e32 v237, v236
	s_nop 0
	v_mul_f32_e32 v236, 0x45800000, v237
	v_cndmask_b32_e32 v236, v237, v236, vcc
	v_mul_f32_e32 v236, 0xbfb8aa3b, v236
	v_mul_f32_e32 v108, v108, v236
	v_mul_f32_e32 v109, v109, v236
	v_mul_f32_e32 v110, v110, v236
	v_mul_f32_e32 v111, v111, v236
	v_exp_f32_e32 v108, v108
	v_exp_f32_e32 v109, v109
	v_exp_f32_e32 v110, v110
	v_exp_f32_e32 v111, v111
	s_nop 0
	v_add_f32_e32 v108, 1.0, v108
	v_add_f32_e32 v109, 1.0, v109
	v_add_f32_e32 v110, 1.0, v110
	v_add_f32_e32 v111, 1.0, v111
	v_rcp_f32_e32 v108, v108
	v_rcp_f32_e32 v109, v109
	v_rcp_f32_e32 v110, v110
	v_rcp_f32_e32 v111, v111
	v_lshlrev_b32_e32 v238, 16, v144
	v_and_b32_e32 v239, 0xffff0000, v144
	v_lshlrev_b32_e32 v240, 16, v148
	v_and_b32_e32 v241, 0xffff0000, v148
	v_pk_fma_f32 v[108:109], v[108:109], v[240:241], v[238:239]
	v_lshlrev_b32_e32 v238, 16, v145
	v_and_b32_e32 v239, 0xffff0000, v145
	v_lshlrev_b32_e32 v240, 16, v149
	v_and_b32_e32 v241, 0xffff0000, v149
	v_pk_fma_f32 v[110:111], v[110:111], v[240:241], v[238:239]
	v_mul_f32_e32 v104, v104, v236
	v_mul_f32_e32 v105, v105, v236
	v_mul_f32_e32 v106, v106, v236
	v_mul_f32_e32 v107, v107, v236
	v_exp_f32_e32 v104, v104
	v_exp_f32_e32 v105, v105
	v_exp_f32_e32 v106, v106
	v_exp_f32_e32 v107, v107
	s_nop 0
	v_add_f32_e32 v104, 1.0, v104
	v_add_f32_e32 v105, 1.0, v105
	v_add_f32_e32 v106, 1.0, v106
	v_add_f32_e32 v107, 1.0, v107
	v_rcp_f32_e32 v104, v104
	v_rcp_f32_e32 v105, v105
	v_rcp_f32_e32 v106, v106
	v_rcp_f32_e32 v107, v107
	v_lshlrev_b32_e32 v238, 16, v146
	v_and_b32_e32 v239, 0xffff0000, v146
	v_lshlrev_b32_e32 v240, 16, v150
	v_and_b32_e32 v241, 0xffff0000, v150
	v_pk_fma_f32 v[104:105], v[104:105], v[240:241], v[238:239]
	v_lshlrev_b32_e32 v238, 16, v147
	v_and_b32_e32 v239, 0xffff0000, v147
	v_lshlrev_b32_e32 v240, 16, v151
	v_and_b32_e32 v241, 0xffff0000, v151
	v_pk_fma_f32 v[106:107], v[106:107], v[240:241], v[238:239]
	v_mul_f32_e32 v100, v100, v236
	v_mul_f32_e32 v101, v101, v236
	v_mul_f32_e32 v102, v102, v236
	v_mul_f32_e32 v103, v103, v236
	v_exp_f32_e32 v100, v100
	v_exp_f32_e32 v101, v101
	v_exp_f32_e32 v102, v102
	v_exp_f32_e32 v103, v103
	s_nop 0
	v_add_f32_e32 v100, 1.0, v100
	v_add_f32_e32 v101, 1.0, v101
	v_add_f32_e32 v102, 1.0, v102
	v_add_f32_e32 v103, 1.0, v103
	v_rcp_f32_e32 v100, v100
	v_rcp_f32_e32 v101, v101
	v_rcp_f32_e32 v102, v102
	v_rcp_f32_e32 v103, v103
	v_lshlrev_b32_e32 v238, 16, v152
	v_and_b32_e32 v239, 0xffff0000, v152
	v_lshlrev_b32_e32 v240, 16, v156
	v_and_b32_e32 v241, 0xffff0000, v156
	v_pk_fma_f32 v[100:101], v[100:101], v[240:241], v[238:239]
	v_lshlrev_b32_e32 v238, 16, v153
	v_and_b32_e32 v239, 0xffff0000, v153
	v_lshlrev_b32_e32 v240, 16, v157
	v_and_b32_e32 v241, 0xffff0000, v157
	v_pk_fma_f32 v[102:103], v[102:103], v[240:241], v[238:239]
	v_mul_f32_e32 v96, v96, v236
	v_mul_f32_e32 v97, v97, v236
	v_mul_f32_e32 v98, v98, v236
	v_mul_f32_e32 v99, v99, v236
	v_exp_f32_e32 v96, v96
	v_exp_f32_e32 v97, v97
	v_exp_f32_e32 v98, v98
	v_exp_f32_e32 v99, v99
	s_nop 0
	v_add_f32_e32 v96, 1.0, v96
	v_add_f32_e32 v97, 1.0, v97
	v_add_f32_e32 v98, 1.0, v98
	v_add_f32_e32 v99, 1.0, v99
	v_rcp_f32_e32 v96, v96
	v_rcp_f32_e32 v97, v97
	v_rcp_f32_e32 v98, v98
	v_rcp_f32_e32 v99, v99
	v_lshlrev_b32_e32 v238, 16, v154
	v_and_b32_e32 v239, 0xffff0000, v154
	v_lshlrev_b32_e32 v240, 16, v158
	v_and_b32_e32 v241, 0xffff0000, v158
	v_pk_fma_f32 v[96:97], v[96:97], v[240:241], v[238:239]
	v_lshlrev_b32_e32 v238, 16, v155
	v_and_b32_e32 v239, 0xffff0000, v155
	v_lshlrev_b32_e32 v240, 16, v159
	v_and_b32_e32 v241, 0xffff0000, v159
	v_pk_fma_f32 v[98:99], v[98:99], v[240:241], v[238:239]
	global_store_dwordx4 v224, v[108:111], s[2:3]
	global_store_dwordx4 v224, v[104:107], s[2:3] offset:16
	global_store_dwordx4 v224, v[100:103], s[2:3] offset:128
	global_store_dwordx4 v224, v[96:99], s[2:3] offset:144
	v_add_u32_e32 v199, 0x240, v193
	global_load_dword v234, v199, s[80:81]
	v_add_u32_e32 v195, 0x90000, v190
	global_load_dwordx4 v[144:147], v195, s[6:7] nt
	global_load_dwordx4 v[148:151], v195, s[8:9] nt
	global_load_dwordx4 v[152:155], v195, s[6:7] offset:64 nt
	global_load_dwordx4 v[156:159], v195, s[8:9] offset:64 nt
	v_add_u32_e32 v189, 0x40000, v192
	s_waitcnt vmcnt(23)
; __device__ __forceinline__ float bflo(unsigned u) { return __uint_as_float(u << 16); }
; __device__ __forceinline__ float bfhi(unsigned u) { return __uint_as_float(u & 0xffff0000u); }
;     __device__ __forceinline__ void operator()(const Acc& acc, const Unit& u, int wr, int wc, int fr, int fq) const {
;     ...
;             for (int m = 0; m < 4; ++m) {
;                 const int row = u.pm * 256 + ai * 128 + wr * 64 + m * 16 + fr;
;                 const float rs = rsqrtf(rsv[m] * (1.0f / DM) + EPS) * -1.4426950408889634f;
; #pragma unroll
;                 for (int bj = 0; bj < 2; ++bj) {
;                     const size_t off = (size_t)row * DM + colbase + 32 * bj;
;                     f32x4 h0 = hv[m][bj][0], h1 = hv[m][bj][1];
;                     const u32x4 p4 = pw[m][bj];
;                     const f32x4 a0 = acc[ai][bj][m][0], a1 = acc[ai][bj][m][1];
;                     h0.x += bflo(p4.x) * __builtin_amdgcn_rcpf(1.0f + __builtin_amdgcn_exp2f(a0.x * rs));
;                     h0.y += bfhi(p4.x) * __builtin_amdgcn_rcpf(1.0f + __builtin_amdgcn_exp2f(a0.y * rs));
;                     h0.z += bflo(p4.y) * __builtin_amdgcn_rcpf(1.0f + __builtin_amdgcn_exp2f(a0.z * rs));
;                     h0.w += bfhi(p4.y) * __builtin_amdgcn_rcpf(1.0f + __builtin_amdgcn_exp2f(a0.w * rs));
;                     h1.x += bflo(p4.z) * __builtin_amdgcn_rcpf(1.0f + __builtin_amdgcn_exp2f(a1.x * rs));
;                     h1.y += bfhi(p4.z) * __builtin_amdgcn_rcpf(1.0f + __builtin_amdgcn_exp2f(a1.y * rs));
;                     h1.z += bflo(p4.w) * __builtin_amdgcn_rcpf(1.0f + __builtin_amdgcn_exp2f(a1.z * rs));
;                     h1.w += bfhi(p4.w) * __builtin_amdgcn_rcpf(1.0f + __builtin_amdgcn_exp2f(a1.w * rs));
;                     *(f32x4*)(out + off) = h0; *(f32x4*)(out + off + 4) = h1;
;                 }
	v_fmamk_f32 v236, v235, 0x3a000000, v205
	v_mul_f32_e32 v237, 0x4b800000, v236
	v_cmp_gt_f32_e32 vcc, s40, v236
	s_nop 1
	v_cndmask_b32_e32 v236, v236, v237, vcc
	v_rsq_f32_e32 v237, v236
	s_nop 0
	v_mul_f32_e32 v236, 0x45800000, v237
	v_cndmask_b32_e32 v236, v237, v236, vcc
	v_mul_f32_e32 v236, 0xbfb8aa3b, v236
	v_mul_f32_e32 v92, v92, v236
	v_mul_f32_e32 v93, v93, v236
	v_mul_f32_e32 v94, v94, v236
	v_mul_f32_e32 v95, v95, v236
	v_exp_f32_e32 v92, v92
	v_exp_f32_e32 v93, v93
	v_exp_f32_e32 v94, v94
	v_exp_f32_e32 v95, v95
	s_nop 0
	v_add_f32_e32 v92, 1.0, v92
	v_add_f32_e32 v93, 1.0, v93
	v_add_f32_e32 v94, 1.0, v94
	v_add_f32_e32 v95, 1.0, v95
	v_rcp_f32_e32 v92, v92
	v_rcp_f32_e32 v93, v93
	v_rcp_f32_e32 v94, v94
	v_rcp_f32_e32 v95, v95
	v_lshlrev_b32_e32 v238, 16, v160
	v_and_b32_e32 v239, 0xffff0000, v160
	v_lshlrev_b32_e32 v240, 16, v164
	v_and_b32_e32 v241, 0xffff0000, v164
	v_pk_fma_f32 v[92:93], v[92:93], v[240:241], v[238:239]
	v_lshlrev_b32_e32 v238, 16, v161
	v_and_b32_e32 v239, 0xffff0000, v161
	v_lshlrev_b32_e32 v240, 16, v165
	v_and_b32_e32 v241, 0xffff0000, v165
	v_pk_fma_f32 v[94:95], v[94:95], v[240:241], v[238:239]
	v_mul_f32_e32 v88, v88, v236
	v_mul_f32_e32 v89, v89, v236
	v_mul_f32_e32 v90, v90, v236
	v_mul_f32_e32 v91, v91, v236
	v_exp_f32_e32 v88, v88
	v_exp_f32_e32 v89, v89
	v_exp_f32_e32 v90, v90
	v_exp_f32_e32 v91, v91
	s_nop 0
	v_add_f32_e32 v88, 1.0, v88
	v_add_f32_e32 v89, 1.0, v89
	v_add_f32_e32 v90, 1.0, v90
	v_add_f32_e32 v91, 1.0, v91
	v_rcp_f32_e32 v88, v88
	v_rcp_f32_e32 v89, v89
	v_rcp_f32_e32 v90, v90
	v_rcp_f32_e32 v91, v91
	v_lshlrev_b32_e32 v238, 16, v162
	v_and_b32_e32 v239, 0xffff0000, v162
	v_lshlrev_b32_e32 v240, 16, v166
	v_and_b32_e32 v241, 0xffff0000, v166
	v_pk_fma_f32 v[88:89], v[88:89], v[240:241], v[238:239]
	v_lshlrev_b32_e32 v238, 16, v163
	v_and_b32_e32 v239, 0xffff0000, v163
	v_lshlrev_b32_e32 v240, 16, v167
	v_and_b32_e32 v241, 0xffff0000, v167
	v_pk_fma_f32 v[90:91], v[90:91], v[240:241], v[238:239]
	v_mul_f32_e32 v84, v84, v236
	v_mul_f32_e32 v85, v85, v236
	v_mul_f32_e32 v86, v86, v236
	v_mul_f32_e32 v87, v87, v236
	v_exp_f32_e32 v84, v84
	v_exp_f32_e32 v85, v85
	v_exp_f32_e32 v86, v86
	v_exp_f32_e32 v87, v87
	s_nop 0
	v_add_f32_e32 v84, 1.0, v84
	v_add_f32_e32 v85, 1.0, v85
	v_add_f32_e32 v86, 1.0, v86
	v_add_f32_e32 v87, 1.0, v87
	v_rcp_f32_e32 v84, v84
	v_rcp_f32_e32 v85, v85
	v_rcp_f32_e32 v86, v86
	v_rcp_f32_e32 v87, v87
	v_lshlrev_b32_e32 v238, 16, v168
	v_and_b32_e32 v239, 0xffff0000, v168
	v_lshlrev_b32_e32 v240, 16, v172
	v_and_b32_e32 v241, 0xffff0000, v172
	v_pk_fma_f32 v[84:85], v[84:85], v[240:241], v[238:239]
	v_lshlrev_b32_e32 v238, 16, v169
	v_and_b32_e32 v239, 0xffff0000, v169
	v_lshlrev_b32_e32 v240, 16, v173
	v_and_b32_e32 v241, 0xffff0000, v173
	v_pk_fma_f32 v[86:87], v[86:87], v[240:241], v[238:239]
	v_mul_f32_e32 v80, v80, v236
	v_mul_f32_e32 v81, v81, v236
	v_mul_f32_e32 v82, v82, v236
	v_mul_f32_e32 v83, v83, v236
	v_exp_f32_e32 v80, v80
	v_exp_f32_e32 v81, v81
	v_exp_f32_e32 v82, v82
	v_exp_f32_e32 v83, v83
	s_nop 0
	v_add_f32_e32 v80, 1.0, v80
	v_add_f32_e32 v81, 1.0, v81
	v_add_f32_e32 v82, 1.0, v82
	v_add_f32_e32 v83, 1.0, v83
	v_rcp_f32_e32 v80, v80
	v_rcp_f32_e32 v81, v81
	v_rcp_f32_e32 v82, v82
	v_rcp_f32_e32 v83, v83
	v_lshlrev_b32_e32 v238, 16, v170
	v_and_b32_e32 v239, 0xffff0000, v170
	v_lshlrev_b32_e32 v240, 16, v174
	v_and_b32_e32 v241, 0xffff0000, v174
	v_pk_fma_f32 v[80:81], v[80:81], v[240:241], v[238:239]
	v_lshlrev_b32_e32 v238, 16, v171
	v_and_b32_e32 v239, 0xffff0000, v171
	v_lshlrev_b32_e32 v240, 16, v175
	v_and_b32_e32 v241, 0xffff0000, v175
	v_pk_fma_f32 v[82:83], v[82:83], v[240:241], v[238:239]
	global_store_dwordx4 v189, v[92:95], s[2:3]
	global_store_dwordx4 v189, v[88:91], s[2:3] offset:16
	global_store_dwordx4 v189, v[84:87], s[2:3] offset:128
	global_store_dwordx4 v189, v[80:83], s[2:3] offset:144
	v_add_u32_e32 v222, 0x280, v193
	global_load_dword v235, v222, s[80:81]
	v_add_u32_e32 v196, 0xa0000, v190
	global_load_dwordx4 v[160:163], v196, s[6:7] nt
	global_load_dwordx4 v[164:167], v196, s[8:9] nt
	global_load_dwordx4 v[168:171], v196, s[6:7] offset:64 nt
	global_load_dwordx4 v[172:175], v196, s[8:9] offset:64 nt
	v_add_u32_e32 v224, 0x60000, v192
	s_waitcnt vmcnt(27)
; __device__ __forceinline__ float bflo(unsigned u) { return __uint_as_float(u << 16); }
; __device__ __forceinline__ float bfhi(unsigned u) { return __uint_as_float(u & 0xffff0000u); }
;     __device__ __forceinline__ void operator()(const Acc& acc, const Unit& u, int wr, int wc, int fr, int fq) const {
;     ...
;             for (int m = 0; m < 4; ++m) {
;                 const int row = u.pm * 256 + ai * 128 + wr * 64 + m * 16 + fr;
;                 const float rs = rsqrtf(rsv[m] * (1.0f / DM) + EPS) * -1.4426950408889634f;
; #pragma unroll
;                 for (int bj = 0; bj < 2; ++bj) {
;                     const size_t off = (size_t)row * DM + colbase + 32 * bj;
;                     f32x4 h0 = hv[m][bj][0], h1 = hv[m][bj][1];
;                     const u32x4 p4 = pw[m][bj];
;                     const f32x4 a0 = acc[ai][bj][m][0], a1 = acc[ai][bj][m][1];
;                     h0.x += bflo(p4.x) * __builtin_amdgcn_rcpf(1.0f + __builtin_amdgcn_exp2f(a0.x * rs));
;                     h0.y += bfhi(p4.x) * __builtin_amdgcn_rcpf(1.0f + __builtin_amdgcn_exp2f(a0.y * rs));
;                     h0.z += bflo(p4.y) * __builtin_amdgcn_rcpf(1.0f + __builtin_amdgcn_exp2f(a0.z * rs));
;                     h0.w += bfhi(p4.y) * __builtin_amdgcn_rcpf(1.0f + __builtin_amdgcn_exp2f(a0.w * rs));
;                     h1.x += bflo(p4.z) * __builtin_amdgcn_rcpf(1.0f + __builtin_amdgcn_exp2f(a1.x * rs));
;                     h1.y += bfhi(p4.z) * __builtin_amdgcn_rcpf(1.0f + __builtin_amdgcn_exp2f(a1.y * rs));
;                     h1.z += bflo(p4.w) * __builtin_amdgcn_rcpf(1.0f + __builtin_amdgcn_exp2f(a1.z * rs));
;                     h1.w += bfhi(p4.w) * __builtin_amdgcn_rcpf(1.0f + __builtin_amdgcn_exp2f(a1.w * rs));
;                     *(f32x4*)(out + off) = h0; *(f32x4*)(out + off + 4) = h1;
;                 }
	v_fmamk_f32 v236, v191, 0x3a000000, v205
	v_mul_f32_e32 v237, 0x4b800000, v236
	v_cmp_gt_f32_e32 vcc, s40, v236
	s_nop 1
	v_cndmask_b32_e32 v236, v236, v237, vcc
	v_rsq_f32_e32 v237, v236
	s_nop 0
	v_mul_f32_e32 v236, 0x45800000, v237
	v_cndmask_b32_e32 v236, v237, v236, vcc
	v_mul_f32_e32 v236, 0xbfb8aa3b, v236
	v_mul_f32_e32 v76, v76, v236
	v_mul_f32_e32 v77, v77, v236
	v_mul_f32_e32 v78, v78, v236
	v_mul_f32_e32 v79, v79, v236
	v_exp_f32_e32 v76, v76
	v_exp_f32_e32 v77, v77
	v_exp_f32_e32 v78, v78
	v_exp_f32_e32 v79, v79
	s_nop 0
	v_add_f32_e32 v76, 1.0, v76
	v_add_f32_e32 v77, 1.0, v77
	v_add_f32_e32 v78, 1.0, v78
	v_add_f32_e32 v79, 1.0, v79
	v_rcp_f32_e32 v76, v76
	v_rcp_f32_e32 v77, v77
	v_rcp_f32_e32 v78, v78
	v_rcp_f32_e32 v79, v79
	v_lshlrev_b32_e32 v238, 16, v206
	v_and_b32_e32 v239, 0xffff0000, v206
	v_lshlrev_b32_e32 v240, 16, v210
	v_and_b32_e32 v241, 0xffff0000, v210
	v_pk_fma_f32 v[76:77], v[76:77], v[240:241], v[238:239]
	v_lshlrev_b32_e32 v238, 16, v207
	v_and_b32_e32 v239, 0xffff0000, v207
	v_lshlrev_b32_e32 v240, 16, v211
	v_and_b32_e32 v241, 0xffff0000, v211
	v_pk_fma_f32 v[78:79], v[78:79], v[240:241], v[238:239]
	v_mul_f32_e32 v72, v72, v236
	v_mul_f32_e32 v73, v73, v236
	v_mul_f32_e32 v74, v74, v236
	v_mul_f32_e32 v75, v75, v236
	v_exp_f32_e32 v72, v72
	v_exp_f32_e32 v73, v73
	v_exp_f32_e32 v74, v74
	v_exp_f32_e32 v75, v75
	s_nop 0
	v_add_f32_e32 v72, 1.0, v72
	v_add_f32_e32 v73, 1.0, v73
	v_add_f32_e32 v74, 1.0, v74
	v_add_f32_e32 v75, 1.0, v75
	v_rcp_f32_e32 v72, v72
	v_rcp_f32_e32 v73, v73
	v_rcp_f32_e32 v74, v74
	v_rcp_f32_e32 v75, v75
	v_lshlrev_b32_e32 v238, 16, v208
	v_and_b32_e32 v239, 0xffff0000, v208
	v_lshlrev_b32_e32 v240, 16, v212
	v_and_b32_e32 v241, 0xffff0000, v212
	v_pk_fma_f32 v[72:73], v[72:73], v[240:241], v[238:239]
	v_lshlrev_b32_e32 v238, 16, v209
	v_and_b32_e32 v239, 0xffff0000, v209
	v_lshlrev_b32_e32 v240, 16, v213
	v_and_b32_e32 v241, 0xffff0000, v213
	v_pk_fma_f32 v[74:75], v[74:75], v[240:241], v[238:239]
	v_mul_f32_e32 v68, v68, v236
	v_mul_f32_e32 v69, v69, v236
	v_mul_f32_e32 v70, v70, v236
	v_mul_f32_e32 v71, v71, v236
	v_exp_f32_e32 v68, v68
	v_exp_f32_e32 v69, v69
	v_exp_f32_e32 v70, v70
	v_exp_f32_e32 v71, v71
	s_nop 0
	v_add_f32_e32 v68, 1.0, v68
	v_add_f32_e32 v69, 1.0, v69
	v_add_f32_e32 v70, 1.0, v70
	v_add_f32_e32 v71, 1.0, v71
	v_rcp_f32_e32 v68, v68
	v_rcp_f32_e32 v69, v69
	v_rcp_f32_e32 v70, v70
	v_rcp_f32_e32 v71, v71
	v_lshlrev_b32_e32 v238, 16, v214
	v_and_b32_e32 v239, 0xffff0000, v214
	v_lshlrev_b32_e32 v240, 16, v218
	v_and_b32_e32 v241, 0xffff0000, v218
	v_pk_fma_f32 v[68:69], v[68:69], v[240:241], v[238:239]
	v_lshlrev_b32_e32 v238, 16, v215
	v_and_b32_e32 v239, 0xffff0000, v215
	v_lshlrev_b32_e32 v240, 16, v219
	v_and_b32_e32 v241, 0xffff0000, v219
	v_pk_fma_f32 v[70:71], v[70:71], v[240:241], v[238:239]
	v_mul_f32_e32 v64, v64, v236
	v_mul_f32_e32 v65, v65, v236
	v_mul_f32_e32 v66, v66, v236
	v_mul_f32_e32 v67, v67, v236
	v_exp_f32_e32 v64, v64
	v_exp_f32_e32 v65, v65
	v_exp_f32_e32 v66, v66
	v_exp_f32_e32 v67, v67
	s_nop 0
	v_add_f32_e32 v64, 1.0, v64
	v_add_f32_e32 v65, 1.0, v65
	v_add_f32_e32 v66, 1.0, v66
	v_add_f32_e32 v67, 1.0, v67
	v_rcp_f32_e32 v64, v64
	v_rcp_f32_e32 v65, v65
	v_rcp_f32_e32 v66, v66
	v_rcp_f32_e32 v67, v67
	v_lshlrev_b32_e32 v238, 16, v216
	v_and_b32_e32 v239, 0xffff0000, v216
	v_lshlrev_b32_e32 v240, 16, v220
	v_and_b32_e32 v241, 0xffff0000, v220
	v_pk_fma_f32 v[64:65], v[64:65], v[240:241], v[238:239]
	v_lshlrev_b32_e32 v238, 16, v217
	v_and_b32_e32 v239, 0xffff0000, v217
	v_lshlrev_b32_e32 v240, 16, v221
	v_and_b32_e32 v241, 0xffff0000, v221
	v_pk_fma_f32 v[66:67], v[66:67], v[240:241], v[238:239]
	global_store_dwordx4 v224, v[76:79], s[2:3]
	global_store_dwordx4 v224, v[72:75], s[2:3] offset:16
	global_store_dwordx4 v224, v[68:71], s[2:3] offset:128
	global_store_dwordx4 v224, v[64:67], s[2:3] offset:144
	v_add_u32_e32 v223, 0x2c0, v193
	global_load_dword v191, v223, s[80:81]
	v_add_u32_e32 v197, 0xb0000, v190
	global_load_dwordx4 v[206:209], v197, s[6:7] nt
	global_load_dwordx4 v[210:213], v197, s[8:9] nt
	global_load_dwordx4 v[214:217], v197, s[6:7] offset:64 nt
	global_load_dwordx4 v[218:221], v197, s[8:9] offset:64 nt
	v_add_u32_e32 v189, 0x100000, v192
	s_waitcnt vmcnt(27)
;     __device__ __forceinline__ void operator()(const Acc& acc, const Unit& u, int wr, int wc, int fr, int fq) const {
;     ...
;         for (int ai = 0; ai < 2; ++ai) {
;             f32x4 hv[4][2][2]; u32x4 pw[4][2]; float rsv[4];
; #pragma unroll
;             for (int m = 0; m < 4; ++m) { const int row = u.pm * 256 + ai * 128 + wr * 64 + m * 16 + fr; const size_t off = (size_t)row * DM + colbase;
;                 rsv[m] = rowss[row];
; #pragma unroll
;                 for (int bj = 0; bj < 2; ++bj) { const u32x4 hw = __builtin_nontemporal_load((const u32x4*)(hin + off + 32 * bj));
;                     hv[m][bj][0] = (f32x4){bflo(hw.x), bfhi(hw.x), bflo(hw.y), bfhi(hw.y)}; hv[m][bj][1] = (f32x4){bflo(hw.z), bfhi(hw.z), bflo(hw.w), bfhi(hw.w)};
;                     pw[m][bj] = __builtin_nontemporal_load((const u32x4*)(PP + off + 32 * bj)); } }
; #pragma unroll
;             for (int m = 0; m < 4; ++m) {
;                 const int row = u.pm * 256 + ai * 128 + wr * 64 + m * 16 + fr;
;                 const float rs = rsqrtf(rsv[m] * (1.0f / DM) + EPS) * -1.4426950408889634f;
; #pragma unroll
;                 for (int bj = 0; bj < 2; ++bj) {
;                     const size_t off = (size_t)row * DM + colbase + 32 * bj;
;                     f32x4 h0 = hv[m][bj][0], h1 = hv[m][bj][1];
;                     const u32x4 p4 = pw[m][bj];
;                     const f32x4 a0 = acc[ai][bj][m][0], a1 = acc[ai][bj][m][1];
;                     h0.x += bflo(p4.x) * __builtin_amdgcn_rcpf(1.0f + __builtin_amdgcn_exp2f(a0.x * rs));
;                     h0.y += bfhi(p4.x) * __builtin_amdgcn_rcpf(1.0f + __builtin_amdgcn_exp2f(a0.y * rs));
;                     h0.z += bflo(p4.y) * __builtin_amdgcn_rcpf(1.0f + __builtin_amdgcn_exp2f(a0.z * rs));
;                     h0.w += bfhi(p4.y) * __builtin_amdgcn_rcpf(1.0f + __builtin_amdgcn_exp2f(a0.w * rs));
;                     h1.x += bflo(p4.z) * __builtin_amdgcn_rcpf(1.0f + __builtin_amdgcn_exp2f(a1.x * rs));
;                     h1.y += bfhi(p4.z) * __builtin_amdgcn_rcpf(1.0f + __builtin_amdgcn_exp2f(a1.y * rs));
;                     h1.z += bflo(p4.w) * __builtin_amdgcn_rcpf(1.0f + __builtin_amdgcn_exp2f(a1.z * rs));
;                     h1.w += bfhi(p4.w) * __builtin_amdgcn_rcpf(1.0f + __builtin_amdgcn_exp2f(a1.w * rs));
;                     *(f32x4*)(out + off) = h0; *(f32x4*)(out + off + 4) = h1;
;                 }
	v_fmamk_f32 v236, v226, 0x3a000000, v205
	v_mul_f32_e32 v237, 0x4b800000, v236
	v_cmp_gt_f32_e32 vcc, s40, v236
	s_nop 1
	v_cndmask_b32_e32 v236, v236, v237, vcc
	v_rsq_f32_e32 v237, v236
	s_nop 0
	v_mul_f32_e32 v236, 0x45800000, v237
	v_cndmask_b32_e32 v236, v237, v236, vcc
	v_mul_f32_e32 v236, 0xbfb8aa3b, v236
	v_mul_f32_e32 v60, v60, v236
	v_mul_f32_e32 v61, v61, v236
	v_mul_f32_e32 v62, v62, v236
	v_mul_f32_e32 v63, v63, v236
	v_exp_f32_e32 v60, v60
	v_exp_f32_e32 v61, v61
	v_exp_f32_e32 v62, v62
	v_exp_f32_e32 v63, v63
	s_nop 0
	v_add_f32_e32 v60, 1.0, v60
	v_add_f32_e32 v61, 1.0, v61
	v_add_f32_e32 v62, 1.0, v62
	v_add_f32_e32 v63, 1.0, v63
	v_rcp_f32_e32 v60, v60
	v_rcp_f32_e32 v61, v61
	v_rcp_f32_e32 v62, v62
	v_rcp_f32_e32 v63, v63
	v_lshlrev_b32_e32 v238, 16, v128
	v_and_b32_e32 v239, 0xffff0000, v128
	v_lshlrev_b32_e32 v240, 16, v132
	v_and_b32_e32 v241, 0xffff0000, v132
	v_pk_fma_f32 v[60:61], v[60:61], v[240:241], v[238:239]
	v_lshlrev_b32_e32 v238, 16, v129
	v_and_b32_e32 v239, 0xffff0000, v129
	v_lshlrev_b32_e32 v240, 16, v133
	v_and_b32_e32 v241, 0xffff0000, v133
	v_pk_fma_f32 v[62:63], v[62:63], v[240:241], v[238:239]
	v_mul_f32_e32 v56, v56, v236
	v_mul_f32_e32 v57, v57, v236
	v_mul_f32_e32 v58, v58, v236
	v_mul_f32_e32 v59, v59, v236
	v_exp_f32_e32 v56, v56
	v_exp_f32_e32 v57, v57
	v_exp_f32_e32 v58, v58
	v_exp_f32_e32 v59, v59
	s_nop 0
	v_add_f32_e32 v56, 1.0, v56
	v_add_f32_e32 v57, 1.0, v57
	v_add_f32_e32 v58, 1.0, v58
	v_add_f32_e32 v59, 1.0, v59
	v_rcp_f32_e32 v56, v56
	v_rcp_f32_e32 v57, v57
	v_rcp_f32_e32 v58, v58
	v_rcp_f32_e32 v59, v59
	v_lshlrev_b32_e32 v238, 16, v130
	v_and_b32_e32 v239, 0xffff0000, v130
	v_lshlrev_b32_e32 v240, 16, v134
	v_and_b32_e32 v241, 0xffff0000, v134
	v_pk_fma_f32 v[56:57], v[56:57], v[240:241], v[238:239]
	v_lshlrev_b32_e32 v238, 16, v131
	v_and_b32_e32 v239, 0xffff0000, v131
	v_lshlrev_b32_e32 v240, 16, v135
	v_and_b32_e32 v241, 0xffff0000, v135
	v_pk_fma_f32 v[58:59], v[58:59], v[240:241], v[238:239]
	v_mul_f32_e32 v52, v52, v236
	v_mul_f32_e32 v53, v53, v236
	v_mul_f32_e32 v54, v54, v236
	v_mul_f32_e32 v55, v55, v236
	v_exp_f32_e32 v52, v52
	v_exp_f32_e32 v53, v53
	v_exp_f32_e32 v54, v54
	v_exp_f32_e32 v55, v55
	s_nop 0
	v_add_f32_e32 v52, 1.0, v52
	v_add_f32_e32 v53, 1.0, v53
	v_add_f32_e32 v54, 1.0, v54
	v_add_f32_e32 v55, 1.0, v55
	v_rcp_f32_e32 v52, v52
	v_rcp_f32_e32 v53, v53
	v_rcp_f32_e32 v54, v54
	v_rcp_f32_e32 v55, v55
	v_lshlrev_b32_e32 v238, 16, v136
	v_and_b32_e32 v239, 0xffff0000, v136
	v_lshlrev_b32_e32 v240, 16, v140
	v_and_b32_e32 v241, 0xffff0000, v140
	v_pk_fma_f32 v[52:53], v[52:53], v[240:241], v[238:239]
	v_lshlrev_b32_e32 v238, 16, v137
	v_and_b32_e32 v239, 0xffff0000, v137
	v_lshlrev_b32_e32 v240, 16, v141
	v_and_b32_e32 v241, 0xffff0000, v141
	v_pk_fma_f32 v[54:55], v[54:55], v[240:241], v[238:239]
	v_mul_f32_e32 v48, v48, v236
	v_mul_f32_e32 v49, v49, v236
	v_mul_f32_e32 v50, v50, v236
	v_mul_f32_e32 v51, v51, v236
	v_exp_f32_e32 v48, v48
	v_exp_f32_e32 v49, v49
	v_exp_f32_e32 v50, v50
	v_exp_f32_e32 v51, v51
	s_nop 0
	v_add_f32_e32 v48, 1.0, v48
	v_add_f32_e32 v49, 1.0, v49
	v_add_f32_e32 v50, 1.0, v50
	v_add_f32_e32 v51, 1.0, v51
	v_rcp_f32_e32 v48, v48
	v_rcp_f32_e32 v49, v49
	v_rcp_f32_e32 v50, v50
	v_rcp_f32_e32 v51, v51
	v_lshlrev_b32_e32 v238, 16, v138
	v_and_b32_e32 v239, 0xffff0000, v138
	v_lshlrev_b32_e32 v240, 16, v142
	v_and_b32_e32 v241, 0xffff0000, v142
	v_pk_fma_f32 v[48:49], v[48:49], v[240:241], v[238:239]
	v_lshlrev_b32_e32 v238, 16, v139
	v_and_b32_e32 v239, 0xffff0000, v139
	v_lshlrev_b32_e32 v240, 16, v143
	v_and_b32_e32 v241, 0xffff0000, v143
	v_pk_fma_f32 v[50:51], v[50:51], v[240:241], v[238:239]
	global_store_dwordx4 v189, v[60:63], s[2:3]
	global_store_dwordx4 v189, v[56:59], s[2:3] offset:16
	global_store_dwordx4 v189, v[52:55], s[2:3] offset:128
	global_store_dwordx4 v189, v[48:51], s[2:3] offset:144
	v_add_u32_e32 v224, 0x120000, v192
	s_waitcnt vmcnt(22)
	v_fmamk_f32 v236, v234, 0x3a000000, v205
	v_mul_f32_e32 v237, 0x4b800000, v236
	v_cmp_gt_f32_e32 vcc, s40, v236
	s_nop 1
	v_cndmask_b32_e32 v236, v236, v237, vcc
	v_rsq_f32_e32 v237, v236
	s_nop 0
	v_mul_f32_e32 v236, 0x45800000, v237
	v_cndmask_b32_e32 v236, v237, v236, vcc
	v_mul_f32_e32 v236, 0xbfb8aa3b, v236
	v_mul_f32_e32 v44, v44, v236
	v_mul_f32_e32 v45, v45, v236
	v_mul_f32_e32 v46, v46, v236
	v_mul_f32_e32 v47, v47, v236
	v_exp_f32_e32 v44, v44
	v_exp_f32_e32 v45, v45
	v_exp_f32_e32 v46, v46
	v_exp_f32_e32 v47, v47
	s_nop 0
	v_add_f32_e32 v44, 1.0, v44
	v_add_f32_e32 v45, 1.0, v45
	v_add_f32_e32 v46, 1.0, v46
	v_add_f32_e32 v47, 1.0, v47
	v_rcp_f32_e32 v44, v44
	v_rcp_f32_e32 v45, v45
	v_rcp_f32_e32 v46, v46
	v_rcp_f32_e32 v47, v47
	v_lshlrev_b32_e32 v238, 16, v144
	v_and_b32_e32 v239, 0xffff0000, v144
	v_lshlrev_b32_e32 v240, 16, v148
	v_and_b32_e32 v241, 0xffff0000, v148
	v_pk_fma_f32 v[44:45], v[44:45], v[240:241], v[238:239]
	v_lshlrev_b32_e32 v238, 16, v145
	v_and_b32_e32 v239, 0xffff0000, v145
	v_lshlrev_b32_e32 v240, 16, v149
	v_and_b32_e32 v241, 0xffff0000, v149
	v_pk_fma_f32 v[46:47], v[46:47], v[240:241], v[238:239]
	v_mul_f32_e32 v40, v40, v236
	v_mul_f32_e32 v41, v41, v236
	v_mul_f32_e32 v42, v42, v236
	v_mul_f32_e32 v43, v43, v236
	v_exp_f32_e32 v40, v40
	v_exp_f32_e32 v41, v41
	v_exp_f32_e32 v42, v42
	v_exp_f32_e32 v43, v43
	s_nop 0
	v_add_f32_e32 v40, 1.0, v40
	v_add_f32_e32 v41, 1.0, v41
	v_add_f32_e32 v42, 1.0, v42
	v_add_f32_e32 v43, 1.0, v43
	v_rcp_f32_e32 v40, v40
	v_rcp_f32_e32 v41, v41
	v_rcp_f32_e32 v42, v42
	v_rcp_f32_e32 v43, v43
	v_lshlrev_b32_e32 v238, 16, v146
	v_and_b32_e32 v239, 0xffff0000, v146
	v_lshlrev_b32_e32 v240, 16, v150
; __device__ __forceinline__ float bflo(unsigned u) { return __uint_as_float(u << 16); }
; __device__ __forceinline__ float bfhi(unsigned u) { return __uint_as_float(u & 0xffff0000u); }
;     __device__ __forceinline__ void operator()(const Acc& acc, const Unit& u, int wr, int wc, int fr, int fq) const {
;     ...
;             for (int m = 0; m < 4; ++m) {
;                 const int row = u.pm * 256 + ai * 128 + wr * 64 + m * 16 + fr;
;                 const float rs = rsqrtf(rsv[m] * (1.0f / DM) + EPS) * -1.4426950408889634f;
; #pragma unroll
;                 for (int bj = 0; bj < 2; ++bj) {
;                     const size_t off = (size_t)row * DM + colbase + 32 * bj;
;                     f32x4 h0 = hv[m][bj][0], h1 = hv[m][bj][1];
;                     const u32x4 p4 = pw[m][bj];
;                     const f32x4 a0 = acc[ai][bj][m][0], a1 = acc[ai][bj][m][1];
;                     h0.x += bflo(p4.x) * __builtin_amdgcn_rcpf(1.0f + __builtin_amdgcn_exp2f(a0.x * rs));
;                     h0.y += bfhi(p4.x) * __builtin_amdgcn_rcpf(1.0f + __builtin_amdgcn_exp2f(a0.y * rs));
;                     h0.z += bflo(p4.y) * __builtin_amdgcn_rcpf(1.0f + __builtin_amdgcn_exp2f(a0.z * rs));
;                     h0.w += bfhi(p4.y) * __builtin_amdgcn_rcpf(1.0f + __builtin_amdgcn_exp2f(a0.w * rs));
;                     h1.x += bflo(p4.z) * __builtin_amdgcn_rcpf(1.0f + __builtin_amdgcn_exp2f(a1.x * rs));
;                     h1.y += bfhi(p4.z) * __builtin_amdgcn_rcpf(1.0f + __builtin_amdgcn_exp2f(a1.y * rs));
;                     h1.z += bflo(p4.w) * __builtin_amdgcn_rcpf(1.0f + __builtin_amdgcn_exp2f(a1.z * rs));
;                     h1.w += bfhi(p4.w) * __builtin_amdgcn_rcpf(1.0f + __builtin_amdgcn_exp2f(a1.w * rs));
;                     *(f32x4*)(out + off) = h0; *(f32x4*)(out + off + 4) = h1;
;                 }
	v_and_b32_e32 v241, 0xffff0000, v150
	v_pk_fma_f32 v[40:41], v[40:41], v[240:241], v[238:239]
	v_lshlrev_b32_e32 v238, 16, v147
	v_and_b32_e32 v239, 0xffff0000, v147
	v_lshlrev_b32_e32 v240, 16, v151
	v_and_b32_e32 v241, 0xffff0000, v151
	v_pk_fma_f32 v[42:43], v[42:43], v[240:241], v[238:239]
	v_mul_f32_e32 v36, v36, v236
	v_mul_f32_e32 v37, v37, v236
	v_mul_f32_e32 v38, v38, v236
	v_mul_f32_e32 v39, v39, v236
	v_exp_f32_e32 v36, v36
	v_exp_f32_e32 v37, v37
	v_exp_f32_e32 v38, v38
	v_exp_f32_e32 v39, v39
	s_nop 0
	v_add_f32_e32 v36, 1.0, v36
	v_add_f32_e32 v37, 1.0, v37
	v_add_f32_e32 v38, 1.0, v38
	v_add_f32_e32 v39, 1.0, v39
	v_rcp_f32_e32 v36, v36
	v_rcp_f32_e32 v37, v37
	v_rcp_f32_e32 v38, v38
	v_rcp_f32_e32 v39, v39
	v_lshlrev_b32_e32 v238, 16, v152
	v_and_b32_e32 v239, 0xffff0000, v152
	v_lshlrev_b32_e32 v240, 16, v156
	v_and_b32_e32 v241, 0xffff0000, v156
	v_pk_fma_f32 v[36:37], v[36:37], v[240:241], v[238:239]
	v_lshlrev_b32_e32 v238, 16, v153
	v_and_b32_e32 v239, 0xffff0000, v153
	v_lshlrev_b32_e32 v240, 16, v157
	v_and_b32_e32 v241, 0xffff0000, v157
	v_pk_fma_f32 v[38:39], v[38:39], v[240:241], v[238:239]
	v_mul_f32_e32 v32, v32, v236
	v_mul_f32_e32 v33, v33, v236
	v_mul_f32_e32 v34, v34, v236
	v_mul_f32_e32 v35, v35, v236
	v_exp_f32_e32 v32, v32
	v_exp_f32_e32 v33, v33
	v_exp_f32_e32 v34, v34
	v_exp_f32_e32 v35, v35
	s_nop 0
	v_add_f32_e32 v32, 1.0, v32
	v_add_f32_e32 v33, 1.0, v33
	v_add_f32_e32 v34, 1.0, v34
	v_add_f32_e32 v35, 1.0, v35
	v_rcp_f32_e32 v32, v32
	v_rcp_f32_e32 v33, v33
	v_rcp_f32_e32 v34, v34
	v_rcp_f32_e32 v35, v35
	v_lshlrev_b32_e32 v238, 16, v154
	v_and_b32_e32 v239, 0xffff0000, v154
	v_lshlrev_b32_e32 v240, 16, v158
	v_and_b32_e32 v241, 0xffff0000, v158
	v_pk_fma_f32 v[32:33], v[32:33], v[240:241], v[238:239]
	v_lshlrev_b32_e32 v238, 16, v155
	v_and_b32_e32 v239, 0xffff0000, v155
	v_lshlrev_b32_e32 v240, 16, v159
	v_and_b32_e32 v241, 0xffff0000, v159
	v_pk_fma_f32 v[34:35], v[34:35], v[240:241], v[238:239]
	global_store_dwordx4 v224, v[44:47], s[2:3]
	global_store_dwordx4 v224, v[40:43], s[2:3] offset:16
	global_store_dwordx4 v224, v[36:39], s[2:3] offset:128
	global_store_dwordx4 v224, v[32:35], s[2:3] offset:144
	v_add_u32_e32 v189, 0x140000, v192
	s_waitcnt vmcnt(17)
	v_fmamk_f32 v236, v235, 0x3a000000, v205
	v_mul_f32_e32 v237, 0x4b800000, v236
	v_cmp_gt_f32_e32 vcc, s40, v236
	s_nop 1
	v_cndmask_b32_e32 v236, v236, v237, vcc
	v_rsq_f32_e32 v237, v236
	s_nop 0
	v_mul_f32_e32 v236, 0x45800000, v237
	v_cndmask_b32_e32 v236, v237, v236, vcc
	v_mul_f32_e32 v236, 0xbfb8aa3b, v236
	v_mul_f32_e32 v28, v28, v236
	v_mul_f32_e32 v29, v29, v236
	v_mul_f32_e32 v30, v30, v236
	v_mul_f32_e32 v31, v31, v236
	v_exp_f32_e32 v28, v28
	v_exp_f32_e32 v29, v29
	v_exp_f32_e32 v30, v30
	v_exp_f32_e32 v31, v31
	s_nop 0
	v_add_f32_e32 v28, 1.0, v28
	v_add_f32_e32 v29, 1.0, v29
	v_add_f32_e32 v30, 1.0, v30
	v_add_f32_e32 v31, 1.0, v31
	v_rcp_f32_e32 v28, v28
	v_rcp_f32_e32 v29, v29
	v_rcp_f32_e32 v30, v30
	v_rcp_f32_e32 v31, v31
	v_lshlrev_b32_e32 v238, 16, v160
	v_and_b32_e32 v239, 0xffff0000, v160
	v_lshlrev_b32_e32 v240, 16, v164
	v_and_b32_e32 v241, 0xffff0000, v164
	v_pk_fma_f32 v[28:29], v[28:29], v[240:241], v[238:239]
	v_lshlrev_b32_e32 v238, 16, v161
	v_and_b32_e32 v239, 0xffff0000, v161
	v_lshlrev_b32_e32 v240, 16, v165
	v_and_b32_e32 v241, 0xffff0000, v165
	v_pk_fma_f32 v[30:31], v[30:31], v[240:241], v[238:239]
	v_mul_f32_e32 v24, v24, v236
	v_mul_f32_e32 v25, v25, v236
	v_mul_f32_e32 v26, v26, v236
	v_mul_f32_e32 v27, v27, v236
	v_exp_f32_e32 v24, v24
	v_exp_f32_e32 v25, v25
	v_exp_f32_e32 v26, v26
	v_exp_f32_e32 v27, v27
	s_nop 0
	v_add_f32_e32 v24, 1.0, v24
	v_add_f32_e32 v25, 1.0, v25
	v_add_f32_e32 v26, 1.0, v26
	v_add_f32_e32 v27, 1.0, v27
	v_rcp_f32_e32 v24, v24
	v_rcp_f32_e32 v25, v25
	v_rcp_f32_e32 v26, v26
	v_rcp_f32_e32 v27, v27
	v_lshlrev_b32_e32 v238, 16, v162
	v_and_b32_e32 v239, 0xffff0000, v162
	v_lshlrev_b32_e32 v240, 16, v166
	v_and_b32_e32 v241, 0xffff0000, v166
	v_pk_fma_f32 v[24:25], v[24:25], v[240:241], v[238:239]
	v_lshlrev_b32_e32 v238, 16, v163
	v_and_b32_e32 v239, 0xffff0000, v163
	v_lshlrev_b32_e32 v240, 16, v167
	v_and_b32_e32 v241, 0xffff0000, v167
	v_pk_fma_f32 v[26:27], v[26:27], v[240:241], v[238:239]
	v_mul_f32_e32 v20, v20, v236
	v_mul_f32_e32 v21, v21, v236
	v_mul_f32_e32 v22, v22, v236
	v_mul_f32_e32 v23, v23, v236
	v_exp_f32_e32 v20, v20
	v_exp_f32_e32 v21, v21
	v_exp_f32_e32 v22, v22
	v_exp_f32_e32 v23, v23
	s_nop 0
	v_add_f32_e32 v20, 1.0, v20
	v_add_f32_e32 v21, 1.0, v21
	v_add_f32_e32 v22, 1.0, v22
	v_add_f32_e32 v23, 1.0, v23
	v_rcp_f32_e32 v20, v20
	v_rcp_f32_e32 v21, v21
	v_rcp_f32_e32 v22, v22
	v_rcp_f32_e32 v23, v23
	v_lshlrev_b32_e32 v238, 16, v168
	v_and_b32_e32 v239, 0xffff0000, v168
	v_lshlrev_b32_e32 v240, 16, v172
	v_and_b32_e32 v241, 0xffff0000, v172
	v_pk_fma_f32 v[20:21], v[20:21], v[240:241], v[238:239]
	v_lshlrev_b32_e32 v238, 16, v169
	v_and_b32_e32 v239, 0xffff0000, v169
	v_lshlrev_b32_e32 v240, 16, v173
	v_and_b32_e32 v241, 0xffff0000, v173
	v_pk_fma_f32 v[22:23], v[22:23], v[240:241], v[238:239]
	v_mul_f32_e32 v16, v16, v236
	v_mul_f32_e32 v17, v17, v236
	v_mul_f32_e32 v18, v18, v236
	v_mul_f32_e32 v19, v19, v236
	v_exp_f32_e32 v16, v16
	v_exp_f32_e32 v17, v17
	v_exp_f32_e32 v18, v18
	v_exp_f32_e32 v19, v19
	s_nop 0
	v_add_f32_e32 v16, 1.0, v16
	v_add_f32_e32 v17, 1.0, v17
	v_add_f32_e32 v18, 1.0, v18
	v_add_f32_e32 v19, 1.0, v19
	v_rcp_f32_e32 v16, v16
	v_rcp_f32_e32 v17, v17
	v_rcp_f32_e32 v18, v18
	v_rcp_f32_e32 v19, v19
	v_lshlrev_b32_e32 v238, 16, v170
	v_and_b32_e32 v239, 0xffff0000, v170
	v_lshlrev_b32_e32 v240, 16, v174
	v_and_b32_e32 v241, 0xffff0000, v174
	v_pk_fma_f32 v[16:17], v[16:17], v[240:241], v[238:239]
	v_lshlrev_b32_e32 v238, 16, v171
	v_and_b32_e32 v239, 0xffff0000, v171
	v_lshlrev_b32_e32 v240, 16, v175
	v_and_b32_e32 v241, 0xffff0000, v175
	v_pk_fma_f32 v[18:19], v[18:19], v[240:241], v[238:239]
	global_store_dwordx4 v189, v[28:31], s[2:3]
	global_store_dwordx4 v189, v[24:27], s[2:3] offset:16
	global_store_dwordx4 v189, v[20:23], s[2:3] offset:128
	global_store_dwordx4 v189, v[16:19], s[2:3] offset:144
	v_add_u32_e32 v224, 0x160000, v192
	s_waitcnt vmcnt(12)
; __device__ __forceinline__ float bflo(unsigned u) { return __uint_as_float(u << 16); }
; __device__ __forceinline__ float bfhi(unsigned u) { return __uint_as_float(u & 0xffff0000u); }
;     __device__ __forceinline__ void operator()(const Acc& acc, const Unit& u, int wr, int wc, int fr, int fq) const {
;     ...
;             for (int m = 0; m < 4; ++m) {
;                 const int row = u.pm * 256 + ai * 128 + wr * 64 + m * 16 + fr;
;                 const float rs = rsqrtf(rsv[m] * (1.0f / DM) + EPS) * -1.4426950408889634f;
; #pragma unroll
;                 for (int bj = 0; bj < 2; ++bj) {
;                     const size_t off = (size_t)row * DM + colbase + 32 * bj;
;                     f32x4 h0 = hv[m][bj][0], h1 = hv[m][bj][1];
;                     const u32x4 p4 = pw[m][bj];
;                     const f32x4 a0 = acc[ai][bj][m][0], a1 = acc[ai][bj][m][1];
;                     h0.x += bflo(p4.x) * __builtin_amdgcn_rcpf(1.0f + __builtin_amdgcn_exp2f(a0.x * rs));
;                     h0.y += bfhi(p4.x) * __builtin_amdgcn_rcpf(1.0f + __builtin_amdgcn_exp2f(a0.y * rs));
;                     h0.z += bflo(p4.y) * __builtin_amdgcn_rcpf(1.0f + __builtin_amdgcn_exp2f(a0.z * rs));
;                     h0.w += bfhi(p4.y) * __builtin_amdgcn_rcpf(1.0f + __builtin_amdgcn_exp2f(a0.w * rs));
;                     h1.x += bflo(p4.z) * __builtin_amdgcn_rcpf(1.0f + __builtin_amdgcn_exp2f(a1.x * rs));
;                     h1.y += bfhi(p4.z) * __builtin_amdgcn_rcpf(1.0f + __builtin_amdgcn_exp2f(a1.y * rs));
;                     h1.z += bflo(p4.w) * __builtin_amdgcn_rcpf(1.0f + __builtin_amdgcn_exp2f(a1.z * rs));
;                     h1.w += bfhi(p4.w) * __builtin_amdgcn_rcpf(1.0f + __builtin_amdgcn_exp2f(a1.w * rs));
;                     *(f32x4*)(out + off) = h0; *(f32x4*)(out + off + 4) = h1;
;                 }
	v_fmamk_f32 v236, v191, 0x3a000000, v205
	v_mul_f32_e32 v237, 0x4b800000, v236
	v_cmp_gt_f32_e32 vcc, s40, v236
	s_nop 1
	v_cndmask_b32_e32 v236, v236, v237, vcc
	v_rsq_f32_e32 v237, v236
	s_nop 0
	v_mul_f32_e32 v236, 0x45800000, v237
	v_cndmask_b32_e32 v236, v237, v236, vcc
	v_mul_f32_e32 v236, 0xbfb8aa3b, v236
	v_mul_f32_e32 v12, v12, v236
	v_mul_f32_e32 v13, v13, v236
	v_mul_f32_e32 v14, v14, v236
	v_mul_f32_e32 v15, v15, v236
	v_exp_f32_e32 v12, v12
	v_exp_f32_e32 v13, v13
	v_exp_f32_e32 v14, v14
	v_exp_f32_e32 v15, v15
	s_nop 0
	v_add_f32_e32 v12, 1.0, v12
	v_add_f32_e32 v13, 1.0, v13
	v_add_f32_e32 v14, 1.0, v14
	v_add_f32_e32 v15, 1.0, v15
	v_rcp_f32_e32 v12, v12
	v_rcp_f32_e32 v13, v13
	v_rcp_f32_e32 v14, v14
	v_rcp_f32_e32 v15, v15
	v_lshlrev_b32_e32 v238, 16, v206
	v_and_b32_e32 v239, 0xffff0000, v206
	v_lshlrev_b32_e32 v240, 16, v210
	v_and_b32_e32 v241, 0xffff0000, v210
	v_pk_fma_f32 v[12:13], v[12:13], v[240:241], v[238:239]
	v_lshlrev_b32_e32 v238, 16, v207
	v_and_b32_e32 v239, 0xffff0000, v207
	v_lshlrev_b32_e32 v240, 16, v211
	v_and_b32_e32 v241, 0xffff0000, v211
	v_pk_fma_f32 v[14:15], v[14:15], v[240:241], v[238:239]
	v_mul_f32_e32 v8, v8, v236
	v_mul_f32_e32 v9, v9, v236
	v_mul_f32_e32 v10, v10, v236
	v_mul_f32_e32 v11, v11, v236
	v_exp_f32_e32 v8, v8
	v_exp_f32_e32 v9, v9
	v_exp_f32_e32 v10, v10
	v_exp_f32_e32 v11, v11
	s_nop 0
	v_add_f32_e32 v8, 1.0, v8
	v_add_f32_e32 v9, 1.0, v9
	v_add_f32_e32 v10, 1.0, v10
	v_add_f32_e32 v11, 1.0, v11
	v_rcp_f32_e32 v8, v8
	v_rcp_f32_e32 v9, v9
	v_rcp_f32_e32 v10, v10
	v_rcp_f32_e32 v11, v11
	v_lshlrev_b32_e32 v238, 16, v208
	v_and_b32_e32 v239, 0xffff0000, v208
	v_lshlrev_b32_e32 v240, 16, v212
	v_and_b32_e32 v241, 0xffff0000, v212
	v_pk_fma_f32 v[8:9], v[8:9], v[240:241], v[238:239]
	v_lshlrev_b32_e32 v238, 16, v209
	v_and_b32_e32 v239, 0xffff0000, v209
	v_lshlrev_b32_e32 v240, 16, v213
	v_and_b32_e32 v241, 0xffff0000, v213
	v_pk_fma_f32 v[10:11], v[10:11], v[240:241], v[238:239]
	v_mul_f32_e32 v4, v4, v236
	v_mul_f32_e32 v5, v5, v236
	v_mul_f32_e32 v6, v6, v236
	v_mul_f32_e32 v7, v7, v236
	v_exp_f32_e32 v4, v4
	v_exp_f32_e32 v5, v5
	v_exp_f32_e32 v6, v6
	v_exp_f32_e32 v7, v7
	s_nop 0
	v_add_f32_e32 v4, 1.0, v4
	v_add_f32_e32 v5, 1.0, v5
	v_add_f32_e32 v6, 1.0, v6
	v_add_f32_e32 v7, 1.0, v7
	v_rcp_f32_e32 v4, v4
	v_rcp_f32_e32 v5, v5
	v_rcp_f32_e32 v6, v6
	v_rcp_f32_e32 v7, v7
	v_lshlrev_b32_e32 v238, 16, v214
	v_and_b32_e32 v239, 0xffff0000, v214
	v_lshlrev_b32_e32 v240, 16, v218
	v_and_b32_e32 v241, 0xffff0000, v218
	v_pk_fma_f32 v[4:5], v[4:5], v[240:241], v[238:239]
	v_lshlrev_b32_e32 v238, 16, v215
	v_and_b32_e32 v239, 0xffff0000, v215
	v_lshlrev_b32_e32 v240, 16, v219
	v_and_b32_e32 v241, 0xffff0000, v219
	v_pk_fma_f32 v[6:7], v[6:7], v[240:241], v[238:239]
	v_mul_f32_e32 v0, v0, v236
	v_mul_f32_e32 v1, v1, v236
	v_mul_f32_e32 v2, v2, v236
	v_mul_f32_e32 v3, v3, v236
	v_exp_f32_e32 v0, v0
	v_exp_f32_e32 v1, v1
	v_exp_f32_e32 v2, v2
	v_exp_f32_e32 v3, v3
	s_nop 0
	v_add_f32_e32 v0, 1.0, v0
	v_add_f32_e32 v1, 1.0, v1
	v_add_f32_e32 v2, 1.0, v2
	v_add_f32_e32 v3, 1.0, v3
	v_rcp_f32_e32 v0, v0
	v_rcp_f32_e32 v1, v1
	v_rcp_f32_e32 v2, v2
	v_rcp_f32_e32 v3, v3
	v_lshlrev_b32_e32 v238, 16, v216
	v_and_b32_e32 v239, 0xffff0000, v216
	v_lshlrev_b32_e32 v240, 16, v220
	v_and_b32_e32 v241, 0xffff0000, v220
	v_pk_fma_f32 v[0:1], v[0:1], v[240:241], v[238:239]
	v_lshlrev_b32_e32 v238, 16, v217
	v_and_b32_e32 v239, 0xffff0000, v217
	v_lshlrev_b32_e32 v240, 16, v221
	v_and_b32_e32 v241, 0xffff0000, v221
	v_pk_fma_f32 v[2:3], v[2:3], v[240:241], v[238:239]
	global_store_dwordx4 v224, v[12:15], s[2:3]
	global_store_dwordx4 v224, v[8:11], s[2:3] offset:16
	global_store_dwordx4 v224, v[4:7], s[2:3] offset:128
	global_store_dwordx4 v224, v[0:3], s[2:3] offset:144
	s_andn2_b64 vcc, exec, s[4:5]
	s_mov_b64 s[4:5], -1
	s_cbranch_vccnz .LBB0_803
	s_and_b64 vcc, exec, s[0:1]
	s_cbranch_vccnz .LBB0_802
	s_barrier
	s_branch .LBB0_802
